# prep_a_prompt gelu+layernorm transpose pass rewritten: 32 row loads issued up front, 4 elements interleaved
# speedup vs baseline: 1.0028x; 1.0028x over previous
; DI bf16_t f2bf(float f) { return (bf16_t)(pk2(f, f) & 0xffffu); }
; DI float gelu_t(float x) { return x * sigm(1.5957691216057308f * (x + 0.044715f * x * x * x)); }
; DI void prep_a_prompt(LAS unsigned char* lds, const Params& P, int l, int unit) {
;     ...
;     {
; #pragma unroll 16
;         for (int i = 0; i < 32; ++i) { const int idx = tid + 512 * i, cch = idx & 127, s = idx >> 7, ch = g * 128 + cch;
;             const float x = gelu_t(P32[(size_t)(row0 + s) * LDP + C_AV + ch]); vt[cch * 136 + s] = f2bf((x - st[2 * s]) * st[2 * s + 1] * lng[ch] + lnb[ch]); }
.LBB0_769:
	s_mul_i32 s6, s5, 0x6800
	s_add_u32 s8, s42, s6
	s_addc_u32 s9, s43, 0
	s_add_u32 s8, s8, 0x800
	s_addc_u32 s9, s9, 0
	v_and_b32_e32 v18, 0x7f, v0
	v_or_b32_e32 v18, s3, v18
	v_lshlrev_b32_e32 v18, 2, v18
	v_lshrrev_b32_e32 v19, 7, v0
	v_lshlrev_b32_e32 v20, 3, v19
	v_lshl_add_u32 v21, v19, 1, v6
	v_mul_u32_u24_e32 v19, 0x6800, v19
	v_add_u32_e32 v18, v18, v19
	global_load_dword v56, v18, s[8:9]
	s_add_u32 s8, s8, 0x1a000
	s_addc_u32 s9, s9, 0
	global_load_dword v57, v18, s[8:9]
	s_add_u32 s8, s8, 0x1a000
	s_addc_u32 s9, s9, 0
	global_load_dword v58, v18, s[8:9]
	s_add_u32 s8, s8, 0x1a000
	s_addc_u32 s9, s9, 0
	global_load_dword v59, v18, s[8:9]
	s_add_u32 s8, s8, 0x1a000
	s_addc_u32 s9, s9, 0
	global_load_dword v60, v18, s[8:9]
	s_add_u32 s8, s8, 0x1a000
	s_addc_u32 s9, s9, 0
	global_load_dword v61, v18, s[8:9]
	s_add_u32 s8, s8, 0x1a000
	s_addc_u32 s9, s9, 0
	global_load_dword v62, v18, s[8:9]
	s_add_u32 s8, s8, 0x1a000
	s_addc_u32 s9, s9, 0
	global_load_dword v63, v18, s[8:9]
	s_add_u32 s8, s8, 0x1a000
	s_addc_u32 s9, s9, 0
	global_load_dword v64, v18, s[8:9]
	s_add_u32 s8, s8, 0x1a000
	s_addc_u32 s9, s9, 0
	global_load_dword v65, v18, s[8:9]
	s_add_u32 s8, s8, 0x1a000
	s_addc_u32 s9, s9, 0
	global_load_dword v66, v18, s[8:9]
	s_add_u32 s8, s8, 0x1a000
	s_addc_u32 s9, s9, 0
	global_load_dword v67, v18, s[8:9]
	s_add_u32 s8, s8, 0x1a000
	s_addc_u32 s9, s9, 0
	global_load_dword v68, v18, s[8:9]
	s_add_u32 s8, s8, 0x1a000
	s_addc_u32 s9, s9, 0
	global_load_dword v69, v18, s[8:9]
	s_add_u32 s8, s8, 0x1a000
	s_addc_u32 s9, s9, 0
	global_load_dword v70, v18, s[8:9]
	s_add_u32 s8, s8, 0x1a000
	s_addc_u32 s9, s9, 0
	global_load_dword v71, v18, s[8:9]
	s_add_u32 s8, s8, 0x1a000
	s_addc_u32 s9, s9, 0
	global_load_dword v72, v18, s[8:9]
	s_add_u32 s8, s8, 0x1a000
	s_addc_u32 s9, s9, 0
	global_load_dword v73, v18, s[8:9]
	s_add_u32 s8, s8, 0x1a000
	s_addc_u32 s9, s9, 0
	global_load_dword v74, v18, s[8:9]
	s_add_u32 s8, s8, 0x1a000
	s_addc_u32 s9, s9, 0
	global_load_dword v75, v18, s[8:9]
	s_add_u32 s8, s8, 0x1a000
	s_addc_u32 s9, s9, 0
	global_load_dword v76, v18, s[8:9]
	s_add_u32 s8, s8, 0x1a000
	s_addc_u32 s9, s9, 0
	global_load_dword v77, v18, s[8:9]
	s_add_u32 s8, s8, 0x1a000
	s_addc_u32 s9, s9, 0
	global_load_dword v78, v18, s[8:9]
	s_add_u32 s8, s8, 0x1a000
	s_addc_u32 s9, s9, 0
	global_load_dword v79, v18, s[8:9]
	s_add_u32 s8, s8, 0x1a000
	s_addc_u32 s9, s9, 0
	global_load_dword v80, v18, s[8:9]
	s_add_u32 s8, s8, 0x1a000
	s_addc_u32 s9, s9, 0
	global_load_dword v81, v18, s[8:9]
	s_add_u32 s8, s8, 0x1a000
	s_addc_u32 s9, s9, 0
	global_load_dword v82, v18, s[8:9]
	s_add_u32 s8, s8, 0x1a000
	s_addc_u32 s9, s9, 0
	global_load_dword v83, v18, s[8:9]
	s_add_u32 s8, s8, 0x1a000
	s_addc_u32 s9, s9, 0
	global_load_dword v84, v18, s[8:9]
	s_add_u32 s8, s8, 0x1a000
	s_addc_u32 s9, s9, 0
	global_load_dword v85, v18, s[8:9]
	s_add_u32 s8, s8, 0x1a000
	s_addc_u32 s9, s9, 0
	global_load_dword v86, v18, s[8:9]
	s_add_u32 s8, s8, 0x1a000
	s_addc_u32 s9, s9, 0
	global_load_dword v87, v18, s[8:9]
	ds_read_b64 v[28:29], v20 offset:0
	ds_read_b64 v[30:31], v20 offset:32
	ds_read_b64 v[32:33], v20 offset:64
	ds_read_b64 v[34:35], v20 offset:96
	s_waitcnt vmcnt(28)
	v_mul_f32_e32 v24, 0x3d372713, v56
	v_mul_f32_e32 v25, 0x3d372713, v57
	v_mul_f32_e32 v26, 0x3d372713, v58
	v_mul_f32_e32 v27, 0x3d372713, v59
	v_mul_f32_e32 v24, v56, v24
	v_mul_f32_e32 v25, v57, v25
	v_mul_f32_e32 v26, v58, v26
	v_mul_f32_e32 v27, v59, v27
	v_fma_f32 v24, v56, v24, v56
	v_fma_f32 v25, v57, v25, v57
	v_fma_f32 v26, v58, v26, v58
	v_fma_f32 v27, v59, v27, v59
	v_mul_f32_e32 v24, 0x3fcc422a, v24
	v_mul_f32_e32 v25, 0x3fcc422a, v25
	v_mul_f32_e32 v26, 0x3fcc422a, v26
	v_mul_f32_e32 v27, 0x3fcc422a, v27
	v_mul_f32_e32 v24, 0xbfb8aa3b, v24
	v_mul_f32_e32 v25, 0xbfb8aa3b, v25
	v_mul_f32_e32 v26, 0xbfb8aa3b, v26
	v_mul_f32_e32 v27, 0xbfb8aa3b, v27
	v_exp_f32_e32 v24, v24
	v_exp_f32_e32 v25, v25
	v_exp_f32_e32 v26, v26
	v_exp_f32_e32 v27, v27
	v_add_f32_e32 v24, 1.0, v24
	v_add_f32_e32 v25, 1.0, v25
	v_add_f32_e32 v26, 1.0, v26
	v_add_f32_e32 v27, 1.0, v27
	v_rcp_f32_e32 v24, v24
	v_rcp_f32_e32 v25, v25
	v_rcp_f32_e32 v26, v26
	v_rcp_f32_e32 v27, v27
	s_waitcnt lgkmcnt(0)
	v_fma_f32 v24, v56, v24, -v28
	v_fma_f32 v25, v57, v25, -v30
	v_fma_f32 v26, v58, v26, -v32
	v_fma_f32 v27, v59, v27, -v34
	v_mul_f32_e32 v24, v29, v24
	v_mul_f32_e32 v25, v31, v25
	v_mul_f32_e32 v26, v33, v26
	v_mul_f32_e32 v27, v35, v27
	v_fma_f32 v24, v4, v24, v5
	v_fma_f32 v25, v4, v25, v5
	v_fma_f32 v26, v4, v26, v5
	v_fma_f32 v27, v4, v27, v5
	v_cvt_pk_bf16_f32 v24, v24, v24
	v_cvt_pk_bf16_f32 v25, v25, v25
	v_cvt_pk_bf16_f32 v26, v26, v26
	v_cvt_pk_bf16_f32 v27, v27, v27
	ds_write_b16 v21, v24 offset:1024
	ds_write_b16 v21, v25 offset:1032
	ds_write_b16 v21, v26 offset:1040
	ds_write_b16 v21, v27 offset:1048
	ds_read_b64 v[28:29], v20 offset:128
	ds_read_b64 v[30:31], v20 offset:160
	ds_read_b64 v[32:33], v20 offset:192
	ds_read_b64 v[34:35], v20 offset:224
	s_waitcnt vmcnt(24)
	v_mul_f32_e32 v24, 0x3d372713, v60
	v_mul_f32_e32 v25, 0x3d372713, v61
	v_mul_f32_e32 v26, 0x3d372713, v62
	v_mul_f32_e32 v27, 0x3d372713, v63
	v_mul_f32_e32 v24, v60, v24
	v_mul_f32_e32 v25, v61, v25
	v_mul_f32_e32 v26, v62, v26
	v_mul_f32_e32 v27, v63, v27
	v_fma_f32 v24, v60, v24, v60
	v_fma_f32 v25, v61, v25, v61
	v_fma_f32 v26, v62, v26, v62
	v_fma_f32 v27, v63, v27, v63
	v_mul_f32_e32 v24, 0x3fcc422a, v24
	v_mul_f32_e32 v25, 0x3fcc422a, v25
	v_mul_f32_e32 v26, 0x3fcc422a, v26
	v_mul_f32_e32 v27, 0x3fcc422a, v27
	v_mul_f32_e32 v24, 0xbfb8aa3b, v24
	v_mul_f32_e32 v25, 0xbfb8aa3b, v25
	v_mul_f32_e32 v26, 0xbfb8aa3b, v26
	v_mul_f32_e32 v27, 0xbfb8aa3b, v27
	v_exp_f32_e32 v24, v24
	v_exp_f32_e32 v25, v25
	v_exp_f32_e32 v26, v26
	v_exp_f32_e32 v27, v27
	v_add_f32_e32 v24, 1.0, v24
	v_add_f32_e32 v25, 1.0, v25
	v_add_f32_e32 v26, 1.0, v26
	v_add_f32_e32 v27, 1.0, v27
	v_rcp_f32_e32 v24, v24
	v_rcp_f32_e32 v25, v25
	v_rcp_f32_e32 v26, v26
	v_rcp_f32_e32 v27, v27
	s_waitcnt lgkmcnt(0)
; DI bf16_t f2bf(float f) { return (bf16_t)(pk2(f, f) & 0xffffu); }
; DI float gelu_t(float x) { return x * sigm(1.5957691216057308f * (x + 0.044715f * x * x * x)); }
; DI void prep_a_prompt(LAS unsigned char* lds, const Params& P, int l, int unit) {
;     ...
;         for (int i = 0; i < 32; ++i) { const int idx = tid + 512 * i, cch = idx & 127, s = idx >> 7, ch = g * 128 + cch;
;             const float x = gelu_t(P32[(size_t)(row0 + s) * LDP + C_AV + ch]); vt[cch * 136 + s] = f2bf((x - st[2 * s]) * st[2 * s + 1] * lng[ch] + lnb[ch]); }
	v_fma_f32 v24, v60, v24, -v28
	v_fma_f32 v25, v61, v25, -v30
	v_fma_f32 v26, v62, v26, -v32
	v_fma_f32 v27, v63, v27, -v34
	v_mul_f32_e32 v24, v29, v24
	v_mul_f32_e32 v25, v31, v25
	v_mul_f32_e32 v26, v33, v26
	v_mul_f32_e32 v27, v35, v27
	v_fma_f32 v24, v4, v24, v5
	v_fma_f32 v25, v4, v25, v5
	v_fma_f32 v26, v4, v26, v5
	v_fma_f32 v27, v4, v27, v5
	v_cvt_pk_bf16_f32 v24, v24, v24
	v_cvt_pk_bf16_f32 v25, v25, v25
	v_cvt_pk_bf16_f32 v26, v26, v26
	v_cvt_pk_bf16_f32 v27, v27, v27
	ds_write_b16 v21, v24 offset:1056
	ds_write_b16 v21, v25 offset:1064
	ds_write_b16 v21, v26 offset:1072
	ds_write_b16 v21, v27 offset:1080
	ds_read_b64 v[28:29], v20 offset:256
	ds_read_b64 v[30:31], v20 offset:288
	ds_read_b64 v[32:33], v20 offset:320
	ds_read_b64 v[34:35], v20 offset:352
	s_waitcnt vmcnt(20)
	v_mul_f32_e32 v24, 0x3d372713, v64
	v_mul_f32_e32 v25, 0x3d372713, v65
	v_mul_f32_e32 v26, 0x3d372713, v66
	v_mul_f32_e32 v27, 0x3d372713, v67
	v_mul_f32_e32 v24, v64, v24
	v_mul_f32_e32 v25, v65, v25
	v_mul_f32_e32 v26, v66, v26
	v_mul_f32_e32 v27, v67, v27
	v_fma_f32 v24, v64, v24, v64
	v_fma_f32 v25, v65, v25, v65
	v_fma_f32 v26, v66, v26, v66
	v_fma_f32 v27, v67, v27, v67
	v_mul_f32_e32 v24, 0x3fcc422a, v24
	v_mul_f32_e32 v25, 0x3fcc422a, v25
	v_mul_f32_e32 v26, 0x3fcc422a, v26
	v_mul_f32_e32 v27, 0x3fcc422a, v27
	v_mul_f32_e32 v24, 0xbfb8aa3b, v24
	v_mul_f32_e32 v25, 0xbfb8aa3b, v25
	v_mul_f32_e32 v26, 0xbfb8aa3b, v26
	v_mul_f32_e32 v27, 0xbfb8aa3b, v27
	v_exp_f32_e32 v24, v24
	v_exp_f32_e32 v25, v25
	v_exp_f32_e32 v26, v26
	v_exp_f32_e32 v27, v27
	v_add_f32_e32 v24, 1.0, v24
	v_add_f32_e32 v25, 1.0, v25
	v_add_f32_e32 v26, 1.0, v26
	v_add_f32_e32 v27, 1.0, v27
	v_rcp_f32_e32 v24, v24
	v_rcp_f32_e32 v25, v25
	v_rcp_f32_e32 v26, v26
	v_rcp_f32_e32 v27, v27
	s_waitcnt lgkmcnt(0)
	v_fma_f32 v24, v64, v24, -v28
	v_fma_f32 v25, v65, v25, -v30
	v_fma_f32 v26, v66, v26, -v32
	v_fma_f32 v27, v67, v27, -v34
	v_mul_f32_e32 v24, v29, v24
	v_mul_f32_e32 v25, v31, v25
	v_mul_f32_e32 v26, v33, v26
	v_mul_f32_e32 v27, v35, v27
	v_fma_f32 v24, v4, v24, v5
	v_fma_f32 v25, v4, v25, v5
	v_fma_f32 v26, v4, v26, v5
	v_fma_f32 v27, v4, v27, v5
	v_cvt_pk_bf16_f32 v24, v24, v24
	v_cvt_pk_bf16_f32 v25, v25, v25
	v_cvt_pk_bf16_f32 v26, v26, v26
	v_cvt_pk_bf16_f32 v27, v27, v27
	ds_write_b16 v21, v24 offset:1088
	ds_write_b16 v21, v25 offset:1096
	ds_write_b16 v21, v26 offset:1104
	ds_write_b16 v21, v27 offset:1112
	ds_read_b64 v[28:29], v20 offset:384
	ds_read_b64 v[30:31], v20 offset:416
	ds_read_b64 v[32:33], v20 offset:448
	ds_read_b64 v[34:35], v20 offset:480
	s_waitcnt vmcnt(16)
	v_mul_f32_e32 v24, 0x3d372713, v68
	v_mul_f32_e32 v25, 0x3d372713, v69
	v_mul_f32_e32 v26, 0x3d372713, v70
	v_mul_f32_e32 v27, 0x3d372713, v71
	v_mul_f32_e32 v24, v68, v24
	v_mul_f32_e32 v25, v69, v25
	v_mul_f32_e32 v26, v70, v26
	v_mul_f32_e32 v27, v71, v27
	v_fma_f32 v24, v68, v24, v68
	v_fma_f32 v25, v69, v25, v69
	v_fma_f32 v26, v70, v26, v70
	v_fma_f32 v27, v71, v27, v71
	v_mul_f32_e32 v24, 0x3fcc422a, v24
	v_mul_f32_e32 v25, 0x3fcc422a, v25
	v_mul_f32_e32 v26, 0x3fcc422a, v26
	v_mul_f32_e32 v27, 0x3fcc422a, v27
	v_mul_f32_e32 v24, 0xbfb8aa3b, v24
	v_mul_f32_e32 v25, 0xbfb8aa3b, v25
	v_mul_f32_e32 v26, 0xbfb8aa3b, v26
	v_mul_f32_e32 v27, 0xbfb8aa3b, v27
	v_exp_f32_e32 v24, v24
	v_exp_f32_e32 v25, v25
	v_exp_f32_e32 v26, v26
	v_exp_f32_e32 v27, v27
	v_add_f32_e32 v24, 1.0, v24
	v_add_f32_e32 v25, 1.0, v25
	v_add_f32_e32 v26, 1.0, v26
	v_add_f32_e32 v27, 1.0, v27
	v_rcp_f32_e32 v24, v24
	v_rcp_f32_e32 v25, v25
	v_rcp_f32_e32 v26, v26
	v_rcp_f32_e32 v27, v27
	s_waitcnt lgkmcnt(0)
	v_fma_f32 v24, v68, v24, -v28
	v_fma_f32 v25, v69, v25, -v30
	v_fma_f32 v26, v70, v26, -v32
	v_fma_f32 v27, v71, v27, -v34
	v_mul_f32_e32 v24, v29, v24
	v_mul_f32_e32 v25, v31, v25
	v_mul_f32_e32 v26, v33, v26
	v_mul_f32_e32 v27, v35, v27
	v_fma_f32 v24, v4, v24, v5
	v_fma_f32 v25, v4, v25, v5
	v_fma_f32 v26, v4, v26, v5
	v_fma_f32 v27, v4, v27, v5
	v_cvt_pk_bf16_f32 v24, v24, v24
	v_cvt_pk_bf16_f32 v25, v25, v25
	v_cvt_pk_bf16_f32 v26, v26, v26
	v_cvt_pk_bf16_f32 v27, v27, v27
	ds_write_b16 v21, v24 offset:1120
	ds_write_b16 v21, v25 offset:1128
	ds_write_b16 v21, v26 offset:1136
	ds_write_b16 v21, v27 offset:1144
	ds_read_b64 v[28:29], v20 offset:512
	ds_read_b64 v[30:31], v20 offset:544
	ds_read_b64 v[32:33], v20 offset:576
	ds_read_b64 v[34:35], v20 offset:608
	s_waitcnt vmcnt(12)
	v_mul_f32_e32 v24, 0x3d372713, v72
	v_mul_f32_e32 v25, 0x3d372713, v73
	v_mul_f32_e32 v26, 0x3d372713, v74
	v_mul_f32_e32 v27, 0x3d372713, v75
	v_mul_f32_e32 v24, v72, v24
	v_mul_f32_e32 v25, v73, v25
	v_mul_f32_e32 v26, v74, v26
	v_mul_f32_e32 v27, v75, v27
	v_fma_f32 v24, v72, v24, v72
	v_fma_f32 v25, v73, v25, v73
	v_fma_f32 v26, v74, v26, v74
	v_fma_f32 v27, v75, v27, v75
	v_mul_f32_e32 v24, 0x3fcc422a, v24
	v_mul_f32_e32 v25, 0x3fcc422a, v25
	v_mul_f32_e32 v26, 0x3fcc422a, v26
	v_mul_f32_e32 v27, 0x3fcc422a, v27
	v_mul_f32_e32 v24, 0xbfb8aa3b, v24
	v_mul_f32_e32 v25, 0xbfb8aa3b, v25
	v_mul_f32_e32 v26, 0xbfb8aa3b, v26
	v_mul_f32_e32 v27, 0xbfb8aa3b, v27
	v_exp_f32_e32 v24, v24
	v_exp_f32_e32 v25, v25
	v_exp_f32_e32 v26, v26
	v_exp_f32_e32 v27, v27
	v_add_f32_e32 v24, 1.0, v24
	v_add_f32_e32 v25, 1.0, v25
	v_add_f32_e32 v26, 1.0, v26
	v_add_f32_e32 v27, 1.0, v27
	v_rcp_f32_e32 v24, v24
	v_rcp_f32_e32 v25, v25
	v_rcp_f32_e32 v26, v26
	v_rcp_f32_e32 v27, v27
	s_waitcnt lgkmcnt(0)
; DI bf16_t f2bf(float f) { return (bf16_t)(pk2(f, f) & 0xffffu); }
; DI float gelu_t(float x) { return x * sigm(1.5957691216057308f * (x + 0.044715f * x * x * x)); }
; DI void prep_a_prompt(LAS unsigned char* lds, const Params& P, int l, int unit) {
;     ...
;         for (int i = 0; i < 32; ++i) { const int idx = tid + 512 * i, cch = idx & 127, s = idx >> 7, ch = g * 128 + cch;
;             const float x = gelu_t(P32[(size_t)(row0 + s) * LDP + C_AV + ch]); vt[cch * 136 + s] = f2bf((x - st[2 * s]) * st[2 * s + 1] * lng[ch] + lnb[ch]); }
;         __syncthreads();
;         const int tt = wave;
;         float uu[8][4];
; #pragma unroll
;         for (int ct = 0; ct < 8; ++ct)
; #pragma unroll
;             for (int j = 0; j < 4; ++j) uu[ct][j] = P32[(size_t)(row0 + tt * 16 + 4 * q + j) * LDP + C_AU + g * 128 + ct * 16 + r];
	v_fma_f32 v24, v72, v24, -v28
	v_fma_f32 v25, v73, v25, -v30
	v_fma_f32 v26, v74, v26, -v32
	v_fma_f32 v27, v75, v27, -v34
	v_mul_f32_e32 v24, v29, v24
	v_mul_f32_e32 v25, v31, v25
	v_mul_f32_e32 v26, v33, v26
	v_mul_f32_e32 v27, v35, v27
	v_fma_f32 v24, v4, v24, v5
	v_fma_f32 v25, v4, v25, v5
	v_fma_f32 v26, v4, v26, v5
	v_fma_f32 v27, v4, v27, v5
	v_cvt_pk_bf16_f32 v24, v24, v24
	v_cvt_pk_bf16_f32 v25, v25, v25
	v_cvt_pk_bf16_f32 v26, v26, v26
	v_cvt_pk_bf16_f32 v27, v27, v27
	ds_write_b16 v21, v24 offset:1152
	ds_write_b16 v21, v25 offset:1160
	ds_write_b16 v21, v26 offset:1168
	ds_write_b16 v21, v27 offset:1176
	ds_read_b64 v[28:29], v20 offset:640
	ds_read_b64 v[30:31], v20 offset:672
	ds_read_b64 v[32:33], v20 offset:704
	ds_read_b64 v[34:35], v20 offset:736
	s_waitcnt vmcnt(8)
	v_mul_f32_e32 v24, 0x3d372713, v76
	v_mul_f32_e32 v25, 0x3d372713, v77
	v_mul_f32_e32 v26, 0x3d372713, v78
	v_mul_f32_e32 v27, 0x3d372713, v79
	v_mul_f32_e32 v24, v76, v24
	v_mul_f32_e32 v25, v77, v25
	v_mul_f32_e32 v26, v78, v26
	v_mul_f32_e32 v27, v79, v27
	v_fma_f32 v24, v76, v24, v76
	v_fma_f32 v25, v77, v25, v77
	v_fma_f32 v26, v78, v26, v78
	v_fma_f32 v27, v79, v27, v79
	v_mul_f32_e32 v24, 0x3fcc422a, v24
	v_mul_f32_e32 v25, 0x3fcc422a, v25
	v_mul_f32_e32 v26, 0x3fcc422a, v26
	v_mul_f32_e32 v27, 0x3fcc422a, v27
	v_mul_f32_e32 v24, 0xbfb8aa3b, v24
	v_mul_f32_e32 v25, 0xbfb8aa3b, v25
	v_mul_f32_e32 v26, 0xbfb8aa3b, v26
	v_mul_f32_e32 v27, 0xbfb8aa3b, v27
	v_exp_f32_e32 v24, v24
	v_exp_f32_e32 v25, v25
	v_exp_f32_e32 v26, v26
	v_exp_f32_e32 v27, v27
	v_add_f32_e32 v24, 1.0, v24
	v_add_f32_e32 v25, 1.0, v25
	v_add_f32_e32 v26, 1.0, v26
	v_add_f32_e32 v27, 1.0, v27
	v_rcp_f32_e32 v24, v24
	v_rcp_f32_e32 v25, v25
	v_rcp_f32_e32 v26, v26
	v_rcp_f32_e32 v27, v27
	s_waitcnt lgkmcnt(0)
	v_fma_f32 v24, v76, v24, -v28
	v_fma_f32 v25, v77, v25, -v30
	v_fma_f32 v26, v78, v26, -v32
	v_fma_f32 v27, v79, v27, -v34
	v_mul_f32_e32 v24, v29, v24
	v_mul_f32_e32 v25, v31, v25
	v_mul_f32_e32 v26, v33, v26
	v_mul_f32_e32 v27, v35, v27
	v_fma_f32 v24, v4, v24, v5
	v_fma_f32 v25, v4, v25, v5
	v_fma_f32 v26, v4, v26, v5
	v_fma_f32 v27, v4, v27, v5
	v_cvt_pk_bf16_f32 v24, v24, v24
	v_cvt_pk_bf16_f32 v25, v25, v25
	v_cvt_pk_bf16_f32 v26, v26, v26
	v_cvt_pk_bf16_f32 v27, v27, v27
	ds_write_b16 v21, v24 offset:1184
	ds_write_b16 v21, v25 offset:1192
	ds_write_b16 v21, v26 offset:1200
	ds_write_b16 v21, v27 offset:1208
	ds_read_b64 v[28:29], v20 offset:768
	ds_read_b64 v[30:31], v20 offset:800
	ds_read_b64 v[32:33], v20 offset:832
	ds_read_b64 v[34:35], v20 offset:864
	s_waitcnt vmcnt(4)
	v_mul_f32_e32 v24, 0x3d372713, v80
	v_mul_f32_e32 v25, 0x3d372713, v81
	v_mul_f32_e32 v26, 0x3d372713, v82
	v_mul_f32_e32 v27, 0x3d372713, v83
	v_mul_f32_e32 v24, v80, v24
	v_mul_f32_e32 v25, v81, v25
	v_mul_f32_e32 v26, v82, v26
	v_mul_f32_e32 v27, v83, v27
	v_fma_f32 v24, v80, v24, v80
	v_fma_f32 v25, v81, v25, v81
	v_fma_f32 v26, v82, v26, v82
	v_fma_f32 v27, v83, v27, v83
	v_mul_f32_e32 v24, 0x3fcc422a, v24
	v_mul_f32_e32 v25, 0x3fcc422a, v25
	v_mul_f32_e32 v26, 0x3fcc422a, v26
	v_mul_f32_e32 v27, 0x3fcc422a, v27
	v_mul_f32_e32 v24, 0xbfb8aa3b, v24
	v_mul_f32_e32 v25, 0xbfb8aa3b, v25
	v_mul_f32_e32 v26, 0xbfb8aa3b, v26
	v_mul_f32_e32 v27, 0xbfb8aa3b, v27
	v_exp_f32_e32 v24, v24
	v_exp_f32_e32 v25, v25
	v_exp_f32_e32 v26, v26
	v_exp_f32_e32 v27, v27
	v_add_f32_e32 v24, 1.0, v24
	v_add_f32_e32 v25, 1.0, v25
	v_add_f32_e32 v26, 1.0, v26
	v_add_f32_e32 v27, 1.0, v27
	v_rcp_f32_e32 v24, v24
	v_rcp_f32_e32 v25, v25
	v_rcp_f32_e32 v26, v26
	v_rcp_f32_e32 v27, v27
	s_waitcnt lgkmcnt(0)
	v_fma_f32 v24, v80, v24, -v28
	v_fma_f32 v25, v81, v25, -v30
	v_fma_f32 v26, v82, v26, -v32
	v_fma_f32 v27, v83, v27, -v34
	v_mul_f32_e32 v24, v29, v24
	v_mul_f32_e32 v25, v31, v25
	v_mul_f32_e32 v26, v33, v26
	v_mul_f32_e32 v27, v35, v27
	v_fma_f32 v24, v4, v24, v5
	v_fma_f32 v25, v4, v25, v5
	v_fma_f32 v26, v4, v26, v5
	v_fma_f32 v27, v4, v27, v5
	v_cvt_pk_bf16_f32 v24, v24, v24
	v_cvt_pk_bf16_f32 v25, v25, v25
	v_cvt_pk_bf16_f32 v26, v26, v26
	v_cvt_pk_bf16_f32 v27, v27, v27
	ds_write_b16 v21, v24 offset:1216
	ds_write_b16 v21, v25 offset:1224
	ds_write_b16 v21, v26 offset:1232
	ds_write_b16 v21, v27 offset:1240
	ds_read_b64 v[28:29], v20 offset:896
	ds_read_b64 v[30:31], v20 offset:928
	ds_read_b64 v[32:33], v20 offset:960
	ds_read_b64 v[34:35], v20 offset:992
	s_waitcnt vmcnt(0)
	v_mul_f32_e32 v24, 0x3d372713, v84
	v_mul_f32_e32 v25, 0x3d372713, v85
	v_mul_f32_e32 v26, 0x3d372713, v86
	v_mul_f32_e32 v27, 0x3d372713, v87
	v_mul_f32_e32 v24, v84, v24
	v_mul_f32_e32 v25, v85, v25
	v_mul_f32_e32 v26, v86, v26
	v_mul_f32_e32 v27, v87, v27
	v_fma_f32 v24, v84, v24, v84
	v_fma_f32 v25, v85, v25, v85
	v_fma_f32 v26, v86, v26, v86
	v_fma_f32 v27, v87, v27, v87
	v_mul_f32_e32 v24, 0x3fcc422a, v24
	v_mul_f32_e32 v25, 0x3fcc422a, v25
	v_mul_f32_e32 v26, 0x3fcc422a, v26
	v_mul_f32_e32 v27, 0x3fcc422a, v27
	v_mul_f32_e32 v24, 0xbfb8aa3b, v24
	v_mul_f32_e32 v25, 0xbfb8aa3b, v25
	v_mul_f32_e32 v26, 0xbfb8aa3b, v26
	v_mul_f32_e32 v27, 0xbfb8aa3b, v27
	v_exp_f32_e32 v24, v24
	v_exp_f32_e32 v25, v25
	v_exp_f32_e32 v26, v26
	v_exp_f32_e32 v27, v27
	v_add_f32_e32 v24, 1.0, v24
	v_add_f32_e32 v25, 1.0, v25
	v_add_f32_e32 v26, 1.0, v26
	v_add_f32_e32 v27, 1.0, v27
	v_rcp_f32_e32 v24, v24
	v_rcp_f32_e32 v25, v25
	v_rcp_f32_e32 v26, v26
	v_rcp_f32_e32 v27, v27
	s_waitcnt lgkmcnt(0)
	v_fma_f32 v24, v84, v24, -v28
	v_fma_f32 v25, v85, v25, -v30
	v_fma_f32 v26, v86, v26, -v32
	v_fma_f32 v27, v87, v27, -v34
	v_mul_f32_e32 v24, v29, v24
	v_mul_f32_e32 v25, v31, v25
	v_mul_f32_e32 v26, v33, v26
	v_mul_f32_e32 v27, v35, v27
	v_fma_f32 v24, v4, v24, v5
	v_fma_f32 v25, v4, v25, v5
	v_fma_f32 v26, v4, v26, v5
	v_fma_f32 v27, v4, v27, v5
	v_cvt_pk_bf16_f32 v24, v24, v24
	v_cvt_pk_bf16_f32 v25, v25, v25
	v_cvt_pk_bf16_f32 v26, v26, v26
	v_cvt_pk_bf16_f32 v27, v27, v27
	ds_write_b16 v21, v24 offset:1248
	ds_write_b16 v21, v25 offset:1256
	ds_write_b16 v21, v26 offset:1264
	ds_write_b16 v21, v27 offset:1272
	s_add_u32 s6, s92, s44
	s_addc_u32 s7, s93, s45
	v_lshrrev_b32_e32 v2, 2, v8
	s_lshl_b32 s8, s3, 2
	v_and_b32_e32 v4, 15, v0
	v_add_u32_e32 v0, s5, v14
	v_and_b32_e32 v5, 12, v2
	s_add_u32 s8, s42, s8
	v_or_b32_e32 v9, v0, v5
	s_addc_u32 s9, s43, 0
	v_lshlrev_b32_e32 v0, 2, v4
	v_lshl_add_u64 v[2:3], s[8:9], 0, v[0:1]
	v_or_b32_e32 v0, 1, v9
	v_mad_i64_i32 v[10:11], s[8:9], v0, s76, v[2:3]
	v_or_b32_e32 v0, 2, v9
	v_mad_i64_i32 v[6:7], s[8:9], v9, s76, v[2:3]
	v_mad_i64_i32 v[12:13], s[8:9], v0, s76, v[2:3]
	v_or_b32_e32 v0, 3, v9
	s_waitcnt lgkmcnt(0)
	s_barrier
; #define LAS __attribute__((address_space(3)))
; DI f32x4 mfma16(bf16x8 a, bf16x8 b, f32x4 c) { return __builtin_amdgcn_mfma_f32_16x16x32_bf16(a, b, c, 0, 0, 0); }
; DI void prep_a_prompt(LAS unsigned char* lds, const Params& P, int l, int unit) {
;     ...
;         const int tt = wave;
;         float uu[8][4];
; #pragma unroll
;         for (int ct = 0; ct < 8; ++ct)
; #pragma unroll
;             for (int j = 0; j < 4; ++j) uu[ct][j] = P32[(size_t)(row0 + tt * 16 + 4 * q + j) * LDP + C_AU + g * 128 + ct * 16 + r];
; #pragma unroll
;         for (int ct = 0; ct < 8; ++ct) { f32x4 acc = {0.f, 0.f, 0.f, 0.f};
; #pragma unroll
;             for (int kk = 0; kk < 4; ++kk) if (kk * 32 <= tt * 16 + 15) {
;                 const bf16x8 a = *(const bf16x8*)(aws + (size_t)(g * 128 + tt * 16 + r) * 128 + kk * 32 + 8 * q); const bf16x8 bb = *(const LAS bf16x8*)(vt + (ct * 16 + r) * 136 + kk * 32 + 8 * q); acc = mfma16(a, bb, acc); }
	v_mad_i64_i32 v[2:3], s[8:9], v0, s76, v[2:3]
	global_load_dword v17, v[6:7], off
	global_load_dword v50, v[6:7], off offset:64
	global_load_dword v46, v[6:7], off offset:128
	global_load_dword v42, v[6:7], off offset:192
	global_load_dword v38, v[6:7], off offset:256
	global_load_dword v34, v[6:7], off offset:320
	global_load_dword v30, v[6:7], off offset:384
	global_load_dword v25, v[6:7], off offset:448
	global_load_dword v16, v[10:11], off
	global_load_dword v49, v[10:11], off offset:64
	global_load_dword v45, v[10:11], off offset:128
	global_load_dword v41, v[10:11], off offset:192
	global_load_dword v37, v[10:11], off offset:256
	global_load_dword v33, v[10:11], off offset:320
	global_load_dword v29, v[10:11], off offset:384
	global_load_dword v24, v[10:11], off offset:448
	global_load_dword v18, v[12:13], off
	global_load_dword v48, v[12:13], off offset:64
	global_load_dword v44, v[12:13], off offset:128
	global_load_dword v40, v[12:13], off offset:192
	global_load_dword v36, v[12:13], off offset:256
	global_load_dword v32, v[12:13], off offset:320
	global_load_dword v28, v[12:13], off offset:384
	global_load_dword v23, v[12:13], off offset:448
	global_load_dword v20, v[2:3], off
	global_load_dword v47, v[2:3], off offset:64
	global_load_dword v43, v[2:3], off offset:128
	global_load_dword v39, v[2:3], off offset:192
	global_load_dword v35, v[2:3], off offset:256
	global_load_dword v31, v[2:3], off offset:320
	global_load_dword v27, v[2:3], off offset:384
	global_load_dword v22, v[2:3], off offset:448
	v_or_b32_e32 v0, s3, v4
	v_add_u32_e32 v2, v0, v14
	v_ashrrev_i32_e32 v3, 31, v2
	v_lshlrev_b64 v[2:3], 8, v[2:3]
	v_lshl_add_u64 v[2:3], s[6:7], 0, v[2:3]
	v_and_b32_e32 v0, 48, v8
	v_lshl_add_u64 v[12:13], v[2:3], 0, v[0:1]
	v_mov_b32_e32 v2, v1
	v_mov_b32_e32 v3, v1
	v_add_u32_e32 v6, 0, v0
	v_mul_u32_u24_e32 v7, 0x110, v4
	v_mov_b32_e32 v0, v1
	v_mov_b64_e32 v[10:11], v[2:3]
	v_cmp_lt_i32_e32 vcc, -1, v15
	v_add_u32_e32 v26, v6, v7
	v_mov_b64_e32 v[8:9], v[0:1]
	s_and_saveexec_b64 s[42:43], vcc
	s_cbranch_execz .LBB0_772
	global_load_dwordx4 v[6:9], v[12:13], off
	ds_read_b128 v[52:55], v26 offset:1024
	s_waitcnt vmcnt(0) lgkmcnt(0)
	v_mfma_f32_16x16x32_bf16 v[8:11], v[6:9], v[52:55], 0
